# final rowpass (f32 out) loop rewritten: 3x unroll with rotating load sets and counted vmcnt
# speedup vs baseline: 1.0131x; 1.0015x over previous
.LBB0_355:
	s_andn2_b64 vcc, exec, s[2:3]
	s_cbranch_vccnz .LBB0_362
	v_mov_b32_e32 v0, v204
	v_cmp_gt_i32_e32 vcc, s28, v32
	s_and_saveexec_b64 s[2:3], vcc
	s_cbranch_execz .LBB0_361
	v_ashrrev_i32_e32 v33, 31, v32
	v_readlane_b32 s4, v254, 32
	v_lshlrev_b32_e32 v0, 2, v0
	v_lshlrev_b64 v[2:3], 11, v[32:33]
	v_readlane_b32 s5, v254, 33
	v_and_b32_e32 v6, 0xfc, v0
	v_lshlrev_b32_e32 v188, 1, v6
	v_lshl_add_u64 v[4:5], s[4:5], 0, v[2:3]
	v_lshl_add_u64 v[2:3], s[88:89], 0, v[2:3]
	v_readlane_b32 s6, v254, 8
	v_lshl_add_u64 v[0:1], v[4:5], 0, v[188:189]
	v_lshl_add_u64 v[2:3], v[2:3], 0, v[188:189]
	v_lshlrev_b32_e32 v38, 2, v6
	v_readlane_b32 s7, v254, 9
	v_add_u32_e32 v22, s70, v32
	global_load_dwordx2 v[112:113], v[0:1], off
	global_load_dwordx2 v[114:115], v[0:1], off offset:512
	global_load_dwordx2 v[116:117], v[0:1], off offset:1024
	global_load_dwordx2 v[118:119], v[0:1], off offset:1536
	global_load_dwordx2 v[120:121], v[2:3], off
	global_load_dwordx2 v[122:123], v[2:3], off offset:512
	global_load_dwordx2 v[124:125], v[2:3], off offset:1024
	global_load_dwordx2 v[126:127], v[2:3], off offset:1536
	v_cmp_gt_i32_e32 vcc, s28, v22
	global_load_dwordx4 v[0:3], v38, s[6:7]
	v_readlane_b32 s6, v254, 10
	v_readlane_b32 s7, v254, 11
	v_cndmask_b32_e32 v22, v32, v22, vcc
	v_ashrrev_i32_e32 v23, 31, v22
	v_lshlrev_b64 v[30:31], 11, v[22:23]
	v_lshl_add_u64 v[22:23], s[88:89], 0, v[30:31]
	v_lshl_add_u64 v[30:31], s[4:5], 0, v[30:31]
	global_load_dwordx4 v[4:7], v38, s[6:7]
	v_readlane_b32 s6, v254, 12
	v_readlane_b32 s7, v254, 13
	v_lshl_add_u64 v[28:29], v[22:23], 0, v[188:189]
	v_lshl_add_u64 v[30:31], v[30:31], 0, v[188:189]
	v_mov_b32_e32 v39, v189
	v_lshl_add_u64 v[36:37], s[88:89], 0, v[188:189]
	s_nop 0
	global_load_dwordx4 v[8:11], v38, s[6:7]
	v_readlane_b32 s6, v254, 14
	v_readlane_b32 s7, v254, 15
	s_nop 4
	global_load_dwordx4 v[12:15], v38, s[6:7]
	global_load_dwordx2 v[142:143], v[28:29], off offset:1536
	global_load_dwordx2 v[140:141], v[28:29], off offset:1024
	global_load_dwordx2 v[138:139], v[28:29], off offset:512
	s_nop 0
	global_load_dwordx2 v[136:137], v[28:29], off
	s_nop 0
	global_load_dwordx2 v[134:135], v[30:31], off offset:1536
	global_load_dwordx2 v[132:133], v[30:31], off offset:1024
	global_load_dwordx2 v[130:131], v[30:31], off offset:512
	global_load_dwordx2 v[128:129], v[30:31], off
	v_readlane_b32 s6, v254, 16
	v_readlane_b32 s7, v254, 17
	v_lshl_add_u64 v[30:31], s[4:5], 0, v[188:189]
	v_lshl_add_u64 v[38:39], s[46:47], 0, v[38:39]
	s_mov_b64 s[4:5], 0
	s_waitcnt vmcnt(0)
	s_branch .LBB0_359
.LBB0_359:
	v_add_u32_e32 v80, s71, v32
	v_cmp_gt_i32_e32 vcc, s28, v80
	s_nop 1
	v_cndmask_b32_e32 v160, v32, v80, vcc
	v_ashrrev_i32_e32 v161, 31, v160
	v_lshlrev_b64 v[160:161], 11, v[160:161]
	v_lshl_add_u64 v[162:163], v[30:31], 0, v[160:161]
	v_lshl_add_u64 v[164:165], v[36:37], 0, v[160:161]
	global_load_dwordx2 v[144:145], v[162:163], off
	global_load_dwordx2 v[146:147], v[162:163], off offset:512
	global_load_dwordx2 v[148:149], v[162:163], off offset:1024
	global_load_dwordx2 v[150:151], v[162:163], off offset:1536
	global_load_dwordx2 v[152:153], v[164:165], off
	global_load_dwordx2 v[154:155], v[164:165], off offset:512
	global_load_dwordx2 v[156:157], v[164:165], off offset:1024
	global_load_dwordx2 v[158:159], v[164:165], off offset:1536
	s_waitcnt vmcnt(24)
	v_lshlrev_b32_e32 v96, 16, v120
	v_and_b32_e32 v97, 0xffff0000, v120
	v_lshlrev_b32_e32 v98, 16, v121
	v_and_b32_e32 v99, 0xffff0000, v121
	v_lshlrev_b32_e32 v100, 16, v122
	v_and_b32_e32 v101, 0xffff0000, v122
	v_lshlrev_b32_e32 v102, 16, v123
	v_and_b32_e32 v103, 0xffff0000, v123
	v_lshlrev_b32_e32 v104, 16, v124
	v_and_b32_e32 v105, 0xffff0000, v124
	v_lshlrev_b32_e32 v106, 16, v125
	v_and_b32_e32 v107, 0xffff0000, v125
	v_lshlrev_b32_e32 v108, 16, v126
	v_and_b32_e32 v109, 0xffff0000, v126
	v_lshlrev_b32_e32 v110, 16, v127
	v_and_b32_e32 v111, 0xffff0000, v127
	v_pk_mul_f32 v[168:169], v[96:97], v[96:97]
	v_pk_mul_f32 v[170:171], v[98:99], v[98:99]
	v_pk_mul_f32 v[172:173], v[100:101], v[100:101]
	v_pk_mul_f32 v[174:175], v[102:103], v[102:103]
	v_pk_mul_f32 v[176:177], v[104:105], v[104:105]
	v_pk_mul_f32 v[178:179], v[106:107], v[106:107]
	v_pk_mul_f32 v[180:181], v[108:109], v[108:109]
	v_pk_mul_f32 v[182:183], v[110:111], v[110:111]
	v_add_f32_e32 v33, v168, v169
	v_add_f32_e32 v33, v170, v33
	v_add_f32_e32 v33, v171, v33
	v_add_f32_e32 v33, v172, v33
	v_add_f32_e32 v33, v173, v33
	v_add_f32_e32 v33, v174, v33
	v_add_f32_e32 v33, v175, v33
	v_add_f32_e32 v33, v176, v33
	v_add_f32_e32 v33, v177, v33
	v_add_f32_e32 v33, v178, v33
	v_add_f32_e32 v33, v179, v33
	v_add_f32_e32 v33, v180, v33
	v_add_f32_e32 v33, v181, v33
	v_add_f32_e32 v33, v182, v33
	v_add_f32_e32 v33, v183, v33
	s_waitcnt lgkmcnt(0)
	v_and_b32_e32 v81, 64, v207
	v_add_u32_e32 v81, 64, v81
	v_xor_b32_e32 v82, 32, v207
	v_cmp_lt_i32_e32 vcc, v82, v81
	s_nop 1
	v_cndmask_b32_e32 v82, v207, v82, vcc
	v_lshlrev_b32_e32 v82, 2, v82
	ds_bpermute_b32 v82, v82, v33
	s_waitcnt lgkmcnt(0)
	v_add_f32_e32 v33, v33, v82
	v_xor_b32_e32 v82, 16, v207
	v_cmp_lt_i32_e32 vcc, v82, v81
	s_nop 1
	v_cndmask_b32_e32 v82, v207, v82, vcc
	v_lshlrev_b32_e32 v82, 2, v82
	ds_bpermute_b32 v82, v82, v33
	s_waitcnt lgkmcnt(0)
	v_add_f32_e32 v33, v33, v82
	v_xor_b32_e32 v82, 8, v207
	v_cmp_lt_i32_e32 vcc, v82, v81
	s_nop 1
	v_cndmask_b32_e32 v82, v207, v82, vcc
	v_lshlrev_b32_e32 v82, 2, v82
	ds_bpermute_b32 v82, v82, v33
	s_waitcnt lgkmcnt(0)
	v_add_f32_e32 v33, v33, v82
	v_xor_b32_e32 v82, 4, v207
	v_cmp_lt_i32_e32 vcc, v82, v81
	s_nop 1
	v_cndmask_b32_e32 v82, v207, v82, vcc
	v_lshlrev_b32_e32 v82, 2, v82
	ds_bpermute_b32 v82, v82, v33
	s_waitcnt lgkmcnt(0)
	v_add_f32_e32 v33, v33, v82
	v_xor_b32_e32 v82, 2, v207
	v_cmp_lt_i32_e32 vcc, v82, v81
	s_nop 1
	v_cndmask_b32_e32 v82, v207, v82, vcc
	v_lshlrev_b32_e32 v82, 2, v82
	ds_bpermute_b32 v82, v82, v33
	s_waitcnt lgkmcnt(0)
	v_add_f32_e32 v33, v33, v82
	v_xor_b32_e32 v82, 1, v207
	v_cmp_lt_i32_e32 vcc, v82, v81
	s_nop 1
	v_cndmask_b32_e32 v81, v207, v82, vcc
	v_lshlrev_b32_e32 v81, 2, v81
	ds_bpermute_b32 v81, v81, v33
	s_andn2_b64 vcc, exec, s[6:7]
	s_cbranch_vccnz .Lrp359_c0
	s_waitcnt lgkmcnt(0)
	v_add_f32_e32 v33, v33, v81
	v_fmamk_f32 v33, v33, 0x3a800000, v205
	v_mul_f32_e32 v81, 0x4b800000, v33
	v_cmp_gt_f32_e32 vcc, s30, v33
	s_nop 1
	v_cndmask_b32_e32 v33, v33, v81, vcc
	v_rsq_f32_e32 v81, v33
	v_ashrrev_i32_e32 v185, 31, v32
	v_mov_b32_e32 v184, v32
	v_lshlrev_b64 v[184:185], 12, v[184:185]
	v_lshl_add_u64 v[84:85], v[38:39], 0, v[184:185]
	v_mul_f32_e32 v166, 0x45800000, v81
	v_cndmask_b32_e32 v166, v81, v166, vcc
	v_pk_mul_f32 v[86:87], v[166:167], v[96:97] op_sel_hi:[0,1]
	v_lshlrev_b32_e32 v88, 16, v112
	v_and_b32_e32 v89, 0xffff0000, v112
	v_pk_mul_f32 v[92:93], v[166:167], v[98:99] op_sel_hi:[0,1]
	v_lshlrev_b32_e32 v90, 16, v113
	v_and_b32_e32 v91, 0xffff0000, v113
	v_pk_fma_f32 v[168:169], v[0:1], v[86:87], v[88:89]
	v_pk_fma_f32 v[170:171], v[2:3], v[92:93], v[90:91]
	global_store_dwordx4 v[84:85], v[168:171], off
	v_pk_mul_f32 v[86:87], v[166:167], v[100:101] op_sel_hi:[0,1]
	v_lshlrev_b32_e32 v88, 16, v114
	v_and_b32_e32 v89, 0xffff0000, v114
	v_pk_mul_f32 v[92:93], v[166:167], v[102:103] op_sel_hi:[0,1]
	v_lshlrev_b32_e32 v90, 16, v115
	v_and_b32_e32 v91, 0xffff0000, v115
	v_pk_fma_f32 v[172:173], v[4:5], v[86:87], v[88:89]
	v_pk_fma_f32 v[174:175], v[6:7], v[92:93], v[90:91]
	global_store_dwordx4 v[84:85], v[172:175], off offset:1024
	v_pk_mul_f32 v[86:87], v[166:167], v[104:105] op_sel_hi:[0,1]
	v_lshlrev_b32_e32 v88, 16, v116
	v_and_b32_e32 v89, 0xffff0000, v116
	v_pk_mul_f32 v[92:93], v[166:167], v[106:107] op_sel_hi:[0,1]
	v_lshlrev_b32_e32 v90, 16, v117
	v_and_b32_e32 v91, 0xffff0000, v117
	v_pk_fma_f32 v[176:177], v[8:9], v[86:87], v[88:89]
	v_pk_fma_f32 v[178:179], v[10:11], v[92:93], v[90:91]
	global_store_dwordx4 v[84:85], v[176:179], off offset:2048
	v_pk_mul_f32 v[86:87], v[166:167], v[108:109] op_sel_hi:[0,1]
	v_lshlrev_b32_e32 v88, 16, v118
	v_and_b32_e32 v89, 0xffff0000, v118
	v_pk_mul_f32 v[92:93], v[166:167], v[110:111] op_sel_hi:[0,1]
	v_lshlrev_b32_e32 v90, 16, v119
	v_and_b32_e32 v91, 0xffff0000, v119
	v_pk_fma_f32 v[180:181], v[12:13], v[86:87], v[88:89]
	v_pk_fma_f32 v[182:183], v[14:15], v[92:93], v[90:91]
	global_store_dwordx4 v[84:85], v[180:183], off offset:3072
.Lrp359_c0:
	v_subrev_u32_e32 v32, s70, v80
	v_cmp_lt_i32_e32 vcc, s31, v32
	s_or_b64 s[4:5], vcc, s[4:5]
	s_andn2_b64 exec, exec, s[4:5]
	s_cbranch_execz .LBB0_361
.Lrp359_top1:
	v_add_u32_e32 v80, s71, v32
	v_cmp_gt_i32_e32 vcc, s28, v80
	s_nop 1
	v_cndmask_b32_e32 v160, v32, v80, vcc
	v_ashrrev_i32_e32 v161, 31, v160
	v_lshlrev_b64 v[160:161], 11, v[160:161]
	v_lshl_add_u64 v[162:163], v[30:31], 0, v[160:161]
	v_lshl_add_u64 v[164:165], v[36:37], 0, v[160:161]
	global_load_dwordx2 v[112:113], v[162:163], off
	global_load_dwordx2 v[114:115], v[162:163], off offset:512
	global_load_dwordx2 v[116:117], v[162:163], off offset:1024
	global_load_dwordx2 v[118:119], v[162:163], off offset:1536
	global_load_dwordx2 v[120:121], v[164:165], off
	global_load_dwordx2 v[122:123], v[164:165], off offset:512
	global_load_dwordx2 v[124:125], v[164:165], off offset:1024
	global_load_dwordx2 v[126:127], v[164:165], off offset:1536
	s_waitcnt vmcnt(24)
	v_lshlrev_b32_e32 v96, 16, v136
	v_and_b32_e32 v97, 0xffff0000, v136
	v_lshlrev_b32_e32 v98, 16, v137
	v_and_b32_e32 v99, 0xffff0000, v137
	v_lshlrev_b32_e32 v100, 16, v138
	v_and_b32_e32 v101, 0xffff0000, v138
	v_lshlrev_b32_e32 v102, 16, v139
	v_and_b32_e32 v103, 0xffff0000, v139
	v_lshlrev_b32_e32 v104, 16, v140
	v_and_b32_e32 v105, 0xffff0000, v140
	v_lshlrev_b32_e32 v106, 16, v141
	v_and_b32_e32 v107, 0xffff0000, v141
	v_lshlrev_b32_e32 v108, 16, v142
	v_and_b32_e32 v109, 0xffff0000, v142
	v_lshlrev_b32_e32 v110, 16, v143
	v_and_b32_e32 v111, 0xffff0000, v143
	v_pk_mul_f32 v[168:169], v[96:97], v[96:97]
	v_pk_mul_f32 v[170:171], v[98:99], v[98:99]
	v_pk_mul_f32 v[172:173], v[100:101], v[100:101]
	v_pk_mul_f32 v[174:175], v[102:103], v[102:103]
	v_pk_mul_f32 v[176:177], v[104:105], v[104:105]
	v_pk_mul_f32 v[178:179], v[106:107], v[106:107]
	v_pk_mul_f32 v[180:181], v[108:109], v[108:109]
	v_pk_mul_f32 v[182:183], v[110:111], v[110:111]
	v_add_f32_e32 v33, v168, v169
	v_add_f32_e32 v33, v170, v33
	v_add_f32_e32 v33, v171, v33
	v_add_f32_e32 v33, v172, v33
	v_add_f32_e32 v33, v173, v33
	v_add_f32_e32 v33, v174, v33
	v_add_f32_e32 v33, v175, v33
	v_add_f32_e32 v33, v176, v33
	v_add_f32_e32 v33, v177, v33
	v_add_f32_e32 v33, v178, v33
	v_add_f32_e32 v33, v179, v33
	v_add_f32_e32 v33, v180, v33
	v_add_f32_e32 v33, v181, v33
	v_add_f32_e32 v33, v182, v33
	v_add_f32_e32 v33, v183, v33
	s_waitcnt lgkmcnt(0)
	v_and_b32_e32 v81, 64, v207
	v_add_u32_e32 v81, 64, v81
	v_xor_b32_e32 v82, 32, v207
	v_cmp_lt_i32_e32 vcc, v82, v81
	s_nop 1
	v_cndmask_b32_e32 v82, v207, v82, vcc
	v_lshlrev_b32_e32 v82, 2, v82
	ds_bpermute_b32 v82, v82, v33
	s_waitcnt lgkmcnt(0)
	v_add_f32_e32 v33, v33, v82
	v_xor_b32_e32 v82, 16, v207
	v_cmp_lt_i32_e32 vcc, v82, v81
	s_nop 1
	v_cndmask_b32_e32 v82, v207, v82, vcc
	v_lshlrev_b32_e32 v82, 2, v82
	ds_bpermute_b32 v82, v82, v33
	s_waitcnt lgkmcnt(0)
	v_add_f32_e32 v33, v33, v82
	v_xor_b32_e32 v82, 8, v207
	v_cmp_lt_i32_e32 vcc, v82, v81
	s_nop 1
	v_cndmask_b32_e32 v82, v207, v82, vcc
	v_lshlrev_b32_e32 v82, 2, v82
	ds_bpermute_b32 v82, v82, v33
	s_waitcnt lgkmcnt(0)
	v_add_f32_e32 v33, v33, v82
	v_xor_b32_e32 v82, 4, v207
	v_cmp_lt_i32_e32 vcc, v82, v81
	s_nop 1
	v_cndmask_b32_e32 v82, v207, v82, vcc
	v_lshlrev_b32_e32 v82, 2, v82
	ds_bpermute_b32 v82, v82, v33
	s_waitcnt lgkmcnt(0)
	v_add_f32_e32 v33, v33, v82
	v_xor_b32_e32 v82, 2, v207
	v_cmp_lt_i32_e32 vcc, v82, v81
	s_nop 1
	v_cndmask_b32_e32 v82, v207, v82, vcc
	v_lshlrev_b32_e32 v82, 2, v82
	ds_bpermute_b32 v82, v82, v33
	s_waitcnt lgkmcnt(0)
	v_add_f32_e32 v33, v33, v82
	v_xor_b32_e32 v82, 1, v207
	v_cmp_lt_i32_e32 vcc, v82, v81
	s_nop 1
	v_cndmask_b32_e32 v81, v207, v82, vcc
	v_lshlrev_b32_e32 v81, 2, v81
	ds_bpermute_b32 v81, v81, v33
	s_andn2_b64 vcc, exec, s[6:7]
	s_cbranch_vccnz .Lrp359_c1
	s_waitcnt lgkmcnt(0)
	v_add_f32_e32 v33, v33, v81
	v_fmamk_f32 v33, v33, 0x3a800000, v205
	v_mul_f32_e32 v81, 0x4b800000, v33
	v_cmp_gt_f32_e32 vcc, s30, v33
	s_nop 1
	v_cndmask_b32_e32 v33, v33, v81, vcc
	v_rsq_f32_e32 v81, v33
	v_ashrrev_i32_e32 v185, 31, v32
	v_mov_b32_e32 v184, v32
	v_lshlrev_b64 v[184:185], 12, v[184:185]
	v_lshl_add_u64 v[84:85], v[38:39], 0, v[184:185]
	v_mul_f32_e32 v166, 0x45800000, v81
	v_cndmask_b32_e32 v166, v81, v166, vcc
	v_pk_mul_f32 v[86:87], v[166:167], v[96:97] op_sel_hi:[0,1]
	v_lshlrev_b32_e32 v88, 16, v128
	v_and_b32_e32 v89, 0xffff0000, v128
	v_pk_mul_f32 v[92:93], v[166:167], v[98:99] op_sel_hi:[0,1]
	v_lshlrev_b32_e32 v90, 16, v129
	v_and_b32_e32 v91, 0xffff0000, v129
	v_pk_fma_f32 v[168:169], v[0:1], v[86:87], v[88:89]
	v_pk_fma_f32 v[170:171], v[2:3], v[92:93], v[90:91]
	global_store_dwordx4 v[84:85], v[168:171], off
	v_pk_mul_f32 v[86:87], v[166:167], v[100:101] op_sel_hi:[0,1]
	v_lshlrev_b32_e32 v88, 16, v130
	v_and_b32_e32 v89, 0xffff0000, v130
	v_pk_mul_f32 v[92:93], v[166:167], v[102:103] op_sel_hi:[0,1]
	v_lshlrev_b32_e32 v90, 16, v131
	v_and_b32_e32 v91, 0xffff0000, v131
	v_pk_fma_f32 v[172:173], v[4:5], v[86:87], v[88:89]
	v_pk_fma_f32 v[174:175], v[6:7], v[92:93], v[90:91]
	global_store_dwordx4 v[84:85], v[172:175], off offset:1024
	v_pk_mul_f32 v[86:87], v[166:167], v[104:105] op_sel_hi:[0,1]
	v_lshlrev_b32_e32 v88, 16, v132
	v_and_b32_e32 v89, 0xffff0000, v132
	v_pk_mul_f32 v[92:93], v[166:167], v[106:107] op_sel_hi:[0,1]
	v_lshlrev_b32_e32 v90, 16, v133
	v_and_b32_e32 v91, 0xffff0000, v133
	v_pk_fma_f32 v[176:177], v[8:9], v[86:87], v[88:89]
	v_pk_fma_f32 v[178:179], v[10:11], v[92:93], v[90:91]
	global_store_dwordx4 v[84:85], v[176:179], off offset:2048
	v_pk_mul_f32 v[86:87], v[166:167], v[108:109] op_sel_hi:[0,1]
	v_lshlrev_b32_e32 v88, 16, v134
	v_and_b32_e32 v89, 0xffff0000, v134
	v_pk_mul_f32 v[92:93], v[166:167], v[110:111] op_sel_hi:[0,1]
	v_lshlrev_b32_e32 v90, 16, v135
	v_and_b32_e32 v91, 0xffff0000, v135
	v_pk_fma_f32 v[180:181], v[12:13], v[86:87], v[88:89]
	v_pk_fma_f32 v[182:183], v[14:15], v[92:93], v[90:91]
	global_store_dwordx4 v[84:85], v[180:183], off offset:3072

.Lrp359_top2:
	v_add_u32_e32 v80, s71, v32
	v_cmp_gt_i32_e32 vcc, s28, v80
	s_nop 1
	v_cndmask_b32_e32 v160, v32, v80, vcc
	v_ashrrev_i32_e32 v161, 31, v160
	v_lshlrev_b64 v[160:161], 11, v[160:161]
	v_lshl_add_u64 v[162:163], v[30:31], 0, v[160:161]
	v_lshl_add_u64 v[164:165], v[36:37], 0, v[160:161]
	global_load_dwordx2 v[128:129], v[162:163], off
	global_load_dwordx2 v[130:131], v[162:163], off offset:512
	global_load_dwordx2 v[132:133], v[162:163], off offset:1024
	global_load_dwordx2 v[134:135], v[162:163], off offset:1536
	global_load_dwordx2 v[136:137], v[164:165], off
	global_load_dwordx2 v[138:139], v[164:165], off offset:512
	global_load_dwordx2 v[140:141], v[164:165], off offset:1024
	global_load_dwordx2 v[142:143], v[164:165], off offset:1536
	s_waitcnt vmcnt(24)
	v_lshlrev_b32_e32 v96, 16, v152
	v_and_b32_e32 v97, 0xffff0000, v152
	v_lshlrev_b32_e32 v98, 16, v153
	v_and_b32_e32 v99, 0xffff0000, v153
	v_lshlrev_b32_e32 v100, 16, v154
	v_and_b32_e32 v101, 0xffff0000, v154
	v_lshlrev_b32_e32 v102, 16, v155
	v_and_b32_e32 v103, 0xffff0000, v155
	v_lshlrev_b32_e32 v104, 16, v156
	v_and_b32_e32 v105, 0xffff0000, v156
	v_lshlrev_b32_e32 v106, 16, v157
	v_and_b32_e32 v107, 0xffff0000, v157
	v_lshlrev_b32_e32 v108, 16, v158
	v_and_b32_e32 v109, 0xffff0000, v158
	v_lshlrev_b32_e32 v110, 16, v159
	v_and_b32_e32 v111, 0xffff0000, v159
	v_pk_mul_f32 v[168:169], v[96:97], v[96:97]
	v_pk_mul_f32 v[170:171], v[98:99], v[98:99]
	v_pk_mul_f32 v[172:173], v[100:101], v[100:101]
	v_pk_mul_f32 v[174:175], v[102:103], v[102:103]
	v_pk_mul_f32 v[176:177], v[104:105], v[104:105]
	v_pk_mul_f32 v[178:179], v[106:107], v[106:107]
	v_pk_mul_f32 v[180:181], v[108:109], v[108:109]
	v_pk_mul_f32 v[182:183], v[110:111], v[110:111]
	v_add_f32_e32 v33, v168, v169
	v_add_f32_e32 v33, v170, v33
	v_add_f32_e32 v33, v171, v33
	v_add_f32_e32 v33, v172, v33
	v_add_f32_e32 v33, v173, v33
	v_add_f32_e32 v33, v174, v33
	v_add_f32_e32 v33, v175, v33
	v_add_f32_e32 v33, v176, v33
	v_add_f32_e32 v33, v177, v33
	v_add_f32_e32 v33, v178, v33
	v_add_f32_e32 v33, v179, v33
	v_add_f32_e32 v33, v180, v33
	v_add_f32_e32 v33, v181, v33
	v_add_f32_e32 v33, v182, v33
	v_add_f32_e32 v33, v183, v33
	s_waitcnt lgkmcnt(0)
	v_and_b32_e32 v81, 64, v207
	v_add_u32_e32 v81, 64, v81
	v_xor_b32_e32 v82, 32, v207
	v_cmp_lt_i32_e32 vcc, v82, v81
	s_nop 1
	v_cndmask_b32_e32 v82, v207, v82, vcc
	v_lshlrev_b32_e32 v82, 2, v82
	ds_bpermute_b32 v82, v82, v33
	s_waitcnt lgkmcnt(0)
	v_add_f32_e32 v33, v33, v82
	v_xor_b32_e32 v82, 16, v207
	v_cmp_lt_i32_e32 vcc, v82, v81
	s_nop 1
	v_cndmask_b32_e32 v82, v207, v82, vcc
	v_lshlrev_b32_e32 v82, 2, v82
	ds_bpermute_b32 v82, v82, v33
	s_waitcnt lgkmcnt(0)
	v_add_f32_e32 v33, v33, v82
	v_xor_b32_e32 v82, 8, v207
	v_cmp_lt_i32_e32 vcc, v82, v81
	s_nop 1
	v_cndmask_b32_e32 v82, v207, v82, vcc
	v_lshlrev_b32_e32 v82, 2, v82
	ds_bpermute_b32 v82, v82, v33
	s_waitcnt lgkmcnt(0)
	v_add_f32_e32 v33, v33, v82
	v_xor_b32_e32 v82, 4, v207
	v_cmp_lt_i32_e32 vcc, v82, v81
	s_nop 1
	v_cndmask_b32_e32 v82, v207, v82, vcc
	v_lshlrev_b32_e32 v82, 2, v82
	ds_bpermute_b32 v82, v82, v33
	s_waitcnt lgkmcnt(0)
	v_add_f32_e32 v33, v33, v82
	v_xor_b32_e32 v82, 2, v207
	v_cmp_lt_i32_e32 vcc, v82, v81
	s_nop 1
	v_cndmask_b32_e32 v82, v207, v82, vcc
	v_lshlrev_b32_e32 v82, 2, v82
	ds_bpermute_b32 v82, v82, v33
	s_waitcnt lgkmcnt(0)
	v_add_f32_e32 v33, v33, v82
	v_xor_b32_e32 v82, 1, v207
	v_cmp_lt_i32_e32 vcc, v82, v81
	s_nop 1
	v_cndmask_b32_e32 v81, v207, v82, vcc
	v_lshlrev_b32_e32 v81, 2, v81
	ds_bpermute_b32 v81, v81, v33
	s_andn2_b64 vcc, exec, s[6:7]
	s_cbranch_vccnz .Lrp359_c2
	s_waitcnt lgkmcnt(0)
	v_add_f32_e32 v33, v33, v81
	v_fmamk_f32 v33, v33, 0x3a800000, v205
	v_mul_f32_e32 v81, 0x4b800000, v33
	v_cmp_gt_f32_e32 vcc, s30, v33
	s_nop 1
	v_cndmask_b32_e32 v33, v33, v81, vcc
	v_rsq_f32_e32 v81, v33
	v_ashrrev_i32_e32 v185, 31, v32
	v_mov_b32_e32 v184, v32
	v_lshlrev_b64 v[184:185], 12, v[184:185]
	v_lshl_add_u64 v[84:85], v[38:39], 0, v[184:185]
	v_mul_f32_e32 v166, 0x45800000, v81
	v_cndmask_b32_e32 v166, v81, v166, vcc
	v_pk_mul_f32 v[86:87], v[166:167], v[96:97] op_sel_hi:[0,1]
	v_lshlrev_b32_e32 v88, 16, v144
	v_and_b32_e32 v89, 0xffff0000, v144
	v_pk_mul_f32 v[92:93], v[166:167], v[98:99] op_sel_hi:[0,1]
	v_lshlrev_b32_e32 v90, 16, v145
	v_and_b32_e32 v91, 0xffff0000, v145
	v_pk_fma_f32 v[168:169], v[0:1], v[86:87], v[88:89]
	v_pk_fma_f32 v[170:171], v[2:3], v[92:93], v[90:91]
	global_store_dwordx4 v[84:85], v[168:171], off
	v_pk_mul_f32 v[86:87], v[166:167], v[100:101] op_sel_hi:[0,1]
	v_lshlrev_b32_e32 v88, 16, v146
	v_and_b32_e32 v89, 0xffff0000, v146
	v_pk_mul_f32 v[92:93], v[166:167], v[102:103] op_sel_hi:[0,1]
	v_lshlrev_b32_e32 v90, 16, v147
	v_and_b32_e32 v91, 0xffff0000, v147
	v_pk_fma_f32 v[172:173], v[4:5], v[86:87], v[88:89]
	v_pk_fma_f32 v[174:175], v[6:7], v[92:93], v[90:91]
	global_store_dwordx4 v[84:85], v[172:175], off offset:1024
	v_pk_mul_f32 v[86:87], v[166:167], v[104:105] op_sel_hi:[0,1]
	v_lshlrev_b32_e32 v88, 16, v148
	v_and_b32_e32 v89, 0xffff0000, v148
	v_pk_mul_f32 v[92:93], v[166:167], v[106:107] op_sel_hi:[0,1]
	v_lshlrev_b32_e32 v90, 16, v149
	v_and_b32_e32 v91, 0xffff0000, v149
	v_pk_fma_f32 v[176:177], v[8:9], v[86:87], v[88:89]
	v_pk_fma_f32 v[178:179], v[10:11], v[92:93], v[90:91]
	global_store_dwordx4 v[84:85], v[176:179], off offset:2048
	v_pk_mul_f32 v[86:87], v[166:167], v[108:109] op_sel_hi:[0,1]
	v_lshlrev_b32_e32 v88, 16, v150
	v_and_b32_e32 v89, 0xffff0000, v150
	v_pk_mul_f32 v[92:93], v[166:167], v[110:111] op_sel_hi:[0,1]
	v_lshlrev_b32_e32 v90, 16, v151
	v_and_b32_e32 v91, 0xffff0000, v151
	v_pk_fma_f32 v[180:181], v[12:13], v[86:87], v[88:89]
	v_pk_fma_f32 v[182:183], v[14:15], v[92:93], v[90:91]
	global_store_dwordx4 v[84:85], v[180:183], off offset:3072
.Lrp359_c2:
	v_subrev_u32_e32 v32, s70, v80
	v_cmp_lt_i32_e32 vcc, s31, v32
	s_or_b64 s[4:5], vcc, s[4:5]
	s_andn2_b64 exec, exec, s[4:5]
	s_cbranch_execz .LBB0_361
	s_branch .LBB0_359
